# P6 fast epilogue: the two elements of a row interleaved (independent exp / rcp chains issued back to back); per-element arithmetic unchanged
# speedup vs baseline: 1.0136x; 1.0136x over previous
; __device__ __forceinline__ u16 f2bf(float f) {
;   unsigned u = __float_as_uint(f);
;   u += 0x7fffu + ((u >> 16) & 1u);
;   return (u16)(u >> 16);
; }
; __device__ __forceinline__ float bf2f(u16 h) { return __uint_as_float(((unsigned)h) << 16); }
; __device__ __forceinline__ unsigned pack2(float a, float b) { return (unsigned)f2bf(a) | ((unsigned)f2bf(b) << 16); }
; __device__ __forceinline__ float wave_sum(float v) {
; #pragma unroll
;   for (int o = 32; o > 0; o >>= 1) v += __shfl_xor(v, o);
;   return v;
; }
; __device__ __forceinline__ float siluf(float x) { return x / (1.f + __expf(-x)); }
; __device__ __forceinline__ void moe_up_tile(const Params& p, char* smem, int l, int e, int nt, int b, int mt, bool isctx) {
;     ...
;   auto epi = [&](f32x4 (&acc)[8][4], int wr, int wc, int fr, int fq) {
; #pragma unroll
;     for (int m = 0; m < 8; ++m)
; #pragma unroll
;       for (int j = 0; j < 4; ++j) {
;         int slot = wr * 128 + m * 16 + fq * 4 + j;
;         if (slot < nvalid) {
;           u16* dst = isctx ? ACTC + ((size_t)(((slot >> 5) * 16 + e) * 32 + (slot & 31))) * 2048 : ACTL + (size_t)slot * 2048;
; #pragma unroll
;           for (int n = 0; n < 2; ++n) {
;             int f = nt * 64 + wc * 32 + n * 16 + fr;
;             float g = acc[m][n][j], uu = acc[m][n + 2][j];
;             dst[f] = f2bf(siluf(g) * uu);
;           }
;         }
;       }
;   };
.LBB0_1673:
	s_or_b64 exec, exec, s[0:1]
	s_lshl_b32 s0, s15, 4
	s_add_i32 s0, s13, s0
	s_ashr_i32 s1, s0, 31
	s_lshl_b64 s[0:1], s[0:1], 22
	s_add_u32 s0, s4, s0
	s_addc_u32 s1, s5, s1
	s_lshl_b32 s6, s11, 12
	s_add_u32 s0, s0, s6
	s_addc_u32 s1, s1, 0
	s_add_u32 s6, s0, 0x2e4e0100
	v_lshlrev_b32_e32 v0, 2, v193
	s_addc_u32 s7, s1, 0
	v_and_b32_e32 v2, 12, v0
	s_add_u32 s4, s4, 0x364e0100
	s_waitcnt lgkmcnt(3)
	v_or_b32_e32 v132, v2, v179
	v_ashrrev_i32_e32 v3, 1, v192
	s_addc_u32 s5, s5, 0
	v_lshl_or_b32 v0, v211, 5, v212
	v_and_b32_e32 v3, 0xffffffc0, v3
	v_cmp_gt_i32_e32 vcc, s14, v132
	s_waitcnt lgkmcnt(0)
	s_barrier
	s_cmpk_lt_i32 s12, 0x1000
	s_cbranch_scc0 .Lp6_epi_slow
	v_lshlrev_b32_e32 v248, 12, v132
	v_lshlrev_b32_e32 v249, 1, v0
	v_lshl_or_b32 v249, s10, 7, v249
	v_add_u32_e32 v248, v248, v249
	v_add_u32_e32 v250, 0x0, v248
	v_mul_f32_e32 v240, 0xbfb8aa3b, v128
	v_mul_f32_e32 v249, 0xbfb8aa3b, v120
	v_exp_f32_e32 v240, v240
	v_exp_f32_e32 v249, v249
	v_add_f32_e32 v240, 1.0, v240
	v_add_f32_e32 v249, 1.0, v249
	v_div_scale_f32 v241, s[8:9], v240, v240, v128
	v_div_scale_f32 v251, s[8:9], v249, v249, v120
	v_rcp_f32_e32 v242, v241
	v_rcp_f32_e32 v252, v251
	v_fma_f32 v243, -v241, v242, 1.0
	v_fma_f32 v253, -v251, v252, 1.0
	v_fmac_f32_e32 v242, v243, v242
	v_fmac_f32_e32 v252, v253, v252
	v_div_scale_f32 v243, vcc, v128, v240, v128
	v_mul_f32_e32 v245, v243, v242
	v_fma_f32 v246, -v241, v245, v243
	v_fmac_f32_e32 v245, v246, v242
	v_fma_f32 v241, -v241, v245, v243
	v_div_fmas_f32 v241, v241, v242, v245
	v_div_fixup_f32 v128, v241, v240, v128
	v_mul_f32_e32 v124, v124, v128
	v_bfe_u32 v128, v124, 16, 1
	v_add3_u32 v124, v124, v128, s33
	global_store_short_d16_hi v250, v124, s[6:7]
	v_div_scale_f32 v253, vcc, v120, v249, v120
	v_mul_f32_e32 v254, v253, v252
	v_fma_f32 v255, -v251, v254, v253
	v_fmac_f32_e32 v254, v255, v252
	v_fma_f32 v251, -v251, v254, v253
	v_div_fmas_f32 v251, v251, v252, v254
	v_div_fixup_f32 v120, v251, v249, v120
	v_mul_f32_e32 v116, v116, v120
	v_bfe_u32 v120, v116, 16, 1
	v_add3_u32 v116, v116, v120, s33
	global_store_short_d16_hi v250, v116, s[6:7] offset:32
	v_add_u32_e32 v250, 0x1000, v248
	v_mul_f32_e32 v240, 0xbfb8aa3b, v129
	v_mul_f32_e32 v249, 0xbfb8aa3b, v121
	v_exp_f32_e32 v240, v240
	v_exp_f32_e32 v249, v249
	v_add_f32_e32 v240, 1.0, v240
	v_add_f32_e32 v249, 1.0, v249
	v_div_scale_f32 v241, s[8:9], v240, v240, v129
	v_div_scale_f32 v251, s[8:9], v249, v249, v121
	v_rcp_f32_e32 v242, v241
	v_rcp_f32_e32 v252, v251
	v_fma_f32 v243, -v241, v242, 1.0
	v_fma_f32 v253, -v251, v252, 1.0
	v_fmac_f32_e32 v242, v243, v242
	v_fmac_f32_e32 v252, v253, v252
	v_div_scale_f32 v243, vcc, v129, v240, v129
	v_mul_f32_e32 v245, v243, v242
	v_fma_f32 v246, -v241, v245, v243
	v_fmac_f32_e32 v245, v246, v242
	v_fma_f32 v241, -v241, v245, v243
	v_div_fmas_f32 v241, v241, v242, v245
	v_div_fixup_f32 v129, v241, v240, v129
	v_mul_f32_e32 v125, v125, v129
	v_bfe_u32 v129, v125, 16, 1
	v_add3_u32 v125, v125, v129, s33
	global_store_short_d16_hi v250, v125, s[6:7]
	v_div_scale_f32 v253, vcc, v121, v249, v121
	v_mul_f32_e32 v254, v253, v252
	v_fma_f32 v255, -v251, v254, v253
	v_fmac_f32_e32 v254, v255, v252
	v_fma_f32 v251, -v251, v254, v253
	v_div_fmas_f32 v251, v251, v252, v254
	v_div_fixup_f32 v121, v251, v249, v121
	v_mul_f32_e32 v117, v117, v121
	v_bfe_u32 v121, v117, 16, 1
	v_add3_u32 v117, v117, v121, s33
	global_store_short_d16_hi v250, v117, s[6:7] offset:32
	v_add_u32_e32 v250, 0x2000, v248
	v_mul_f32_e32 v240, 0xbfb8aa3b, v130
	v_mul_f32_e32 v249, 0xbfb8aa3b, v122
	v_exp_f32_e32 v240, v240
	v_exp_f32_e32 v249, v249
	v_add_f32_e32 v240, 1.0, v240
	v_add_f32_e32 v249, 1.0, v249
	v_div_scale_f32 v241, s[8:9], v240, v240, v130
	v_div_scale_f32 v251, s[8:9], v249, v249, v122
	v_rcp_f32_e32 v242, v241
	v_rcp_f32_e32 v252, v251
	v_fma_f32 v243, -v241, v242, 1.0
	v_fma_f32 v253, -v251, v252, 1.0
	v_fmac_f32_e32 v242, v243, v242
	v_fmac_f32_e32 v252, v253, v252
	v_div_scale_f32 v243, vcc, v130, v240, v130
	v_mul_f32_e32 v245, v243, v242
	v_fma_f32 v246, -v241, v245, v243
	v_fmac_f32_e32 v245, v246, v242
	v_fma_f32 v241, -v241, v245, v243
	v_div_fmas_f32 v241, v241, v242, v245
	v_div_fixup_f32 v130, v241, v240, v130
	v_mul_f32_e32 v126, v126, v130
	v_bfe_u32 v130, v126, 16, 1
	v_add3_u32 v126, v126, v130, s33
	global_store_short_d16_hi v250, v126, s[6:7]
	v_div_scale_f32 v253, vcc, v122, v249, v122
	v_mul_f32_e32 v254, v253, v252
	v_fma_f32 v255, -v251, v254, v253
	v_fmac_f32_e32 v254, v255, v252
	v_fma_f32 v251, -v251, v254, v253
	v_div_fmas_f32 v251, v251, v252, v254
	v_div_fixup_f32 v122, v251, v249, v122
	v_mul_f32_e32 v118, v118, v122
	v_bfe_u32 v122, v118, 16, 1
	v_add3_u32 v118, v118, v122, s33
	global_store_short_d16_hi v250, v118, s[6:7] offset:32
	v_add_u32_e32 v250, 0x3000, v248
	v_mul_f32_e32 v240, 0xbfb8aa3b, v131
	v_mul_f32_e32 v249, 0xbfb8aa3b, v123
	v_exp_f32_e32 v240, v240
	v_exp_f32_e32 v249, v249
	v_add_f32_e32 v240, 1.0, v240
	v_add_f32_e32 v249, 1.0, v249
	v_div_scale_f32 v241, s[8:9], v240, v240, v131
	v_div_scale_f32 v251, s[8:9], v249, v249, v123
	v_rcp_f32_e32 v242, v241
	v_rcp_f32_e32 v252, v251
	v_fma_f32 v243, -v241, v242, 1.0
	v_fma_f32 v253, -v251, v252, 1.0
	v_fmac_f32_e32 v242, v243, v242
	v_fmac_f32_e32 v252, v253, v252
	v_div_scale_f32 v243, vcc, v131, v240, v131
	v_mul_f32_e32 v245, v243, v242
	v_fma_f32 v246, -v241, v245, v243
	v_fmac_f32_e32 v245, v246, v242
	v_fma_f32 v241, -v241, v245, v243
	v_div_fmas_f32 v241, v241, v242, v245
	v_div_fixup_f32 v131, v241, v240, v131
	v_mul_f32_e32 v127, v127, v131
	v_bfe_u32 v131, v127, 16, 1
	v_add3_u32 v127, v127, v131, s33
; __device__ __forceinline__ u16 f2bf(float f) {
;   unsigned u = __float_as_uint(f);
;   u += 0x7fffu + ((u >> 16) & 1u);
;   return (u16)(u >> 16);
; }
; __device__ __forceinline__ float bf2f(u16 h) { return __uint_as_float(((unsigned)h) << 16); }
; __device__ __forceinline__ unsigned pack2(float a, float b) { return (unsigned)f2bf(a) | ((unsigned)f2bf(b) << 16); }
; __device__ __forceinline__ float wave_sum(float v) {
; #pragma unroll
;   for (int o = 32; o > 0; o >>= 1) v += __shfl_xor(v, o);
;   return v;
; }
; __device__ __forceinline__ float siluf(float x) { return x / (1.f + __expf(-x)); }
; __device__ __forceinline__ void moe_up_tile(const Params& p, char* smem, int l, int e, int nt, int b, int mt, bool isctx) {
;     ...
;   auto epi = [&](f32x4 (&acc)[8][4], int wr, int wc, int fr, int fq) {
; #pragma unroll
;     for (int m = 0; m < 8; ++m)
; #pragma unroll
;       for (int j = 0; j < 4; ++j) {
;         int slot = wr * 128 + m * 16 + fq * 4 + j;
;         if (slot < nvalid) {
;           u16* dst = isctx ? ACTC + ((size_t)(((slot >> 5) * 16 + e) * 32 + (slot & 31))) * 2048 : ACTL + (size_t)slot * 2048;
; #pragma unroll
;           for (int n = 0; n < 2; ++n) {
;             int f = nt * 64 + wc * 32 + n * 16 + fr;
;             float g = acc[m][n][j], uu = acc[m][n + 2][j];
;             dst[f] = f2bf(siluf(g) * uu);
;           }
;         }
;       }
;   };
	global_store_short_d16_hi v250, v127, s[6:7]
	v_div_scale_f32 v253, vcc, v123, v249, v123
	v_mul_f32_e32 v254, v253, v252
	v_fma_f32 v255, -v251, v254, v253
	v_fmac_f32_e32 v254, v255, v252
	v_fma_f32 v251, -v251, v254, v253
	v_div_fmas_f32 v251, v251, v252, v254
	v_div_fixup_f32 v123, v251, v249, v123
	v_mul_f32_e32 v119, v119, v123
	v_bfe_u32 v123, v119, 16, 1
	v_add3_u32 v119, v119, v123, s33
	global_store_short_d16_hi v250, v119, s[6:7] offset:32
	v_add_u32_e32 v250, 0x10000, v248
	v_mul_f32_e32 v240, 0xbfb8aa3b, v112
	v_mul_f32_e32 v249, 0xbfb8aa3b, v104
	v_exp_f32_e32 v240, v240
	v_exp_f32_e32 v249, v249
	v_add_f32_e32 v240, 1.0, v240
	v_add_f32_e32 v249, 1.0, v249
	v_div_scale_f32 v241, s[8:9], v240, v240, v112
	v_div_scale_f32 v251, s[8:9], v249, v249, v104
	v_rcp_f32_e32 v242, v241
	v_rcp_f32_e32 v252, v251
	v_fma_f32 v243, -v241, v242, 1.0
	v_fma_f32 v253, -v251, v252, 1.0
	v_fmac_f32_e32 v242, v243, v242
	v_fmac_f32_e32 v252, v253, v252
	v_div_scale_f32 v243, vcc, v112, v240, v112
	v_mul_f32_e32 v245, v243, v242
	v_fma_f32 v246, -v241, v245, v243
	v_fmac_f32_e32 v245, v246, v242
	v_fma_f32 v241, -v241, v245, v243
	v_div_fmas_f32 v241, v241, v242, v245
	v_div_fixup_f32 v112, v241, v240, v112
	v_mul_f32_e32 v108, v108, v112
	v_bfe_u32 v112, v108, 16, 1
	v_add3_u32 v108, v108, v112, s33
	global_store_short_d16_hi v250, v108, s[6:7]
	v_div_scale_f32 v253, vcc, v104, v249, v104
	v_mul_f32_e32 v254, v253, v252
	v_fma_f32 v255, -v251, v254, v253
	v_fmac_f32_e32 v254, v255, v252
	v_fma_f32 v251, -v251, v254, v253
	v_div_fmas_f32 v251, v251, v252, v254
	v_div_fixup_f32 v104, v251, v249, v104
	v_mul_f32_e32 v100, v100, v104
	v_bfe_u32 v104, v100, 16, 1
	v_add3_u32 v100, v100, v104, s33
	global_store_short_d16_hi v250, v100, s[6:7] offset:32
	v_add_u32_e32 v250, 0x11000, v248
	v_mul_f32_e32 v240, 0xbfb8aa3b, v113
	v_mul_f32_e32 v249, 0xbfb8aa3b, v105
	v_exp_f32_e32 v240, v240
	v_exp_f32_e32 v249, v249
	v_add_f32_e32 v240, 1.0, v240
	v_add_f32_e32 v249, 1.0, v249
	v_div_scale_f32 v241, s[8:9], v240, v240, v113
	v_div_scale_f32 v251, s[8:9], v249, v249, v105
	v_rcp_f32_e32 v242, v241
	v_rcp_f32_e32 v252, v251
	v_fma_f32 v243, -v241, v242, 1.0
	v_fma_f32 v253, -v251, v252, 1.0
	v_fmac_f32_e32 v242, v243, v242
	v_fmac_f32_e32 v252, v253, v252
	v_div_scale_f32 v243, vcc, v113, v240, v113
	v_mul_f32_e32 v245, v243, v242
	v_fma_f32 v246, -v241, v245, v243
	v_fmac_f32_e32 v245, v246, v242
	v_fma_f32 v241, -v241, v245, v243
	v_div_fmas_f32 v241, v241, v242, v245
	v_div_fixup_f32 v113, v241, v240, v113
	v_mul_f32_e32 v109, v109, v113
	v_bfe_u32 v113, v109, 16, 1
	v_add3_u32 v109, v109, v113, s33
	global_store_short_d16_hi v250, v109, s[6:7]
	v_div_scale_f32 v253, vcc, v105, v249, v105
	v_mul_f32_e32 v254, v253, v252
	v_fma_f32 v255, -v251, v254, v253
	v_fmac_f32_e32 v254, v255, v252
	v_fma_f32 v251, -v251, v254, v253
	v_div_fmas_f32 v251, v251, v252, v254
	v_div_fixup_f32 v105, v251, v249, v105
	v_mul_f32_e32 v101, v101, v105
	v_bfe_u32 v105, v101, 16, 1
	v_add3_u32 v101, v101, v105, s33
	global_store_short_d16_hi v250, v101, s[6:7] offset:32
	v_add_u32_e32 v250, 0x12000, v248
	v_mul_f32_e32 v240, 0xbfb8aa3b, v114
	v_mul_f32_e32 v249, 0xbfb8aa3b, v106
	v_exp_f32_e32 v240, v240
	v_exp_f32_e32 v249, v249
	v_add_f32_e32 v240, 1.0, v240
	v_add_f32_e32 v249, 1.0, v249
	v_div_scale_f32 v241, s[8:9], v240, v240, v114
	v_div_scale_f32 v251, s[8:9], v249, v249, v106
	v_rcp_f32_e32 v242, v241
	v_rcp_f32_e32 v252, v251
	v_fma_f32 v243, -v241, v242, 1.0
	v_fma_f32 v253, -v251, v252, 1.0
	v_fmac_f32_e32 v242, v243, v242
	v_fmac_f32_e32 v252, v253, v252
	v_div_scale_f32 v243, vcc, v114, v240, v114
	v_mul_f32_e32 v245, v243, v242
	v_fma_f32 v246, -v241, v245, v243
	v_fmac_f32_e32 v245, v246, v242
	v_fma_f32 v241, -v241, v245, v243
	v_div_fmas_f32 v241, v241, v242, v245
	v_div_fixup_f32 v114, v241, v240, v114
	v_mul_f32_e32 v110, v110, v114
	v_bfe_u32 v114, v110, 16, 1
	v_add3_u32 v110, v110, v114, s33
	global_store_short_d16_hi v250, v110, s[6:7]
	v_div_scale_f32 v253, vcc, v106, v249, v106
	v_mul_f32_e32 v254, v253, v252
	v_fma_f32 v255, -v251, v254, v253
	v_fmac_f32_e32 v254, v255, v252
	v_fma_f32 v251, -v251, v254, v253
	v_div_fmas_f32 v251, v251, v252, v254
	v_div_fixup_f32 v106, v251, v249, v106
	v_mul_f32_e32 v102, v102, v106
	v_bfe_u32 v106, v102, 16, 1
	v_add3_u32 v102, v102, v106, s33
	global_store_short_d16_hi v250, v102, s[6:7] offset:32
	v_add_u32_e32 v250, 0x13000, v248
	v_mul_f32_e32 v240, 0xbfb8aa3b, v115
	v_mul_f32_e32 v249, 0xbfb8aa3b, v107
	v_exp_f32_e32 v240, v240
	v_exp_f32_e32 v249, v249
	v_add_f32_e32 v240, 1.0, v240
	v_add_f32_e32 v249, 1.0, v249
	v_div_scale_f32 v241, s[8:9], v240, v240, v115
	v_div_scale_f32 v251, s[8:9], v249, v249, v107
	v_rcp_f32_e32 v242, v241
	v_rcp_f32_e32 v252, v251
	v_fma_f32 v243, -v241, v242, 1.0
	v_fma_f32 v253, -v251, v252, 1.0
	v_fmac_f32_e32 v242, v243, v242
	v_fmac_f32_e32 v252, v253, v252
	v_div_scale_f32 v243, vcc, v115, v240, v115
	v_mul_f32_e32 v245, v243, v242
	v_fma_f32 v246, -v241, v245, v243
	v_fmac_f32_e32 v245, v246, v242
	v_fma_f32 v241, -v241, v245, v243
	v_div_fmas_f32 v241, v241, v242, v245
	v_div_fixup_f32 v115, v241, v240, v115
	v_mul_f32_e32 v111, v111, v115
	v_bfe_u32 v115, v111, 16, 1
	v_add3_u32 v111, v111, v115, s33
	global_store_short_d16_hi v250, v111, s[6:7]
	v_div_scale_f32 v253, vcc, v107, v249, v107
	v_mul_f32_e32 v254, v253, v252
	v_fma_f32 v255, -v251, v254, v253
	v_fmac_f32_e32 v254, v255, v252
	v_fma_f32 v251, -v251, v254, v253
	v_div_fmas_f32 v251, v251, v252, v254
	v_div_fixup_f32 v107, v251, v249, v107
	v_mul_f32_e32 v103, v103, v107
	v_bfe_u32 v107, v103, 16, 1
; __device__ __forceinline__ u16 f2bf(float f) {
;   unsigned u = __float_as_uint(f);
;   u += 0x7fffu + ((u >> 16) & 1u);
;   return (u16)(u >> 16);
; }
; __device__ __forceinline__ float bf2f(u16 h) { return __uint_as_float(((unsigned)h) << 16); }
; __device__ __forceinline__ unsigned pack2(float a, float b) { return (unsigned)f2bf(a) | ((unsigned)f2bf(b) << 16); }
; __device__ __forceinline__ float wave_sum(float v) {
; #pragma unroll
;   for (int o = 32; o > 0; o >>= 1) v += __shfl_xor(v, o);
;   return v;
; }
; __device__ __forceinline__ float siluf(float x) { return x / (1.f + __expf(-x)); }
; __device__ __forceinline__ void moe_up_tile(const Params& p, char* smem, int l, int e, int nt, int b, int mt, bool isctx) {
;     ...
;   auto epi = [&](f32x4 (&acc)[8][4], int wr, int wc, int fr, int fq) {
; #pragma unroll
;     for (int m = 0; m < 8; ++m)
; #pragma unroll
;       for (int j = 0; j < 4; ++j) {
;         int slot = wr * 128 + m * 16 + fq * 4 + j;
;         if (slot < nvalid) {
;           u16* dst = isctx ? ACTC + ((size_t)(((slot >> 5) * 16 + e) * 32 + (slot & 31))) * 2048 : ACTL + (size_t)slot * 2048;
; #pragma unroll
;           for (int n = 0; n < 2; ++n) {
;             int f = nt * 64 + wc * 32 + n * 16 + fr;
;             float g = acc[m][n][j], uu = acc[m][n + 2][j];
;             dst[f] = f2bf(siluf(g) * uu);
;           }
;         }
;       }
;   };
	v_add3_u32 v103, v103, v107, s33
	global_store_short_d16_hi v250, v103, s[6:7] offset:32
	v_add_u32_e32 v250, 0x20000, v248
	v_mul_f32_e32 v240, 0xbfb8aa3b, v96
	v_mul_f32_e32 v249, 0xbfb8aa3b, v88
	v_exp_f32_e32 v240, v240
	v_exp_f32_e32 v249, v249
	v_add_f32_e32 v240, 1.0, v240
	v_add_f32_e32 v249, 1.0, v249
	v_div_scale_f32 v241, s[8:9], v240, v240, v96
	v_div_scale_f32 v251, s[8:9], v249, v249, v88
	v_rcp_f32_e32 v242, v241
	v_rcp_f32_e32 v252, v251
	v_fma_f32 v243, -v241, v242, 1.0
	v_fma_f32 v253, -v251, v252, 1.0
	v_fmac_f32_e32 v242, v243, v242
	v_fmac_f32_e32 v252, v253, v252
	v_div_scale_f32 v243, vcc, v96, v240, v96
	v_mul_f32_e32 v245, v243, v242
	v_fma_f32 v246, -v241, v245, v243
	v_fmac_f32_e32 v245, v246, v242
	v_fma_f32 v241, -v241, v245, v243
	v_div_fmas_f32 v241, v241, v242, v245
	v_div_fixup_f32 v96, v241, v240, v96
	v_mul_f32_e32 v92, v92, v96
	v_bfe_u32 v96, v92, 16, 1
	v_add3_u32 v92, v92, v96, s33
	global_store_short_d16_hi v250, v92, s[6:7]
	v_div_scale_f32 v253, vcc, v88, v249, v88
	v_mul_f32_e32 v254, v253, v252
	v_fma_f32 v255, -v251, v254, v253
	v_fmac_f32_e32 v254, v255, v252
	v_fma_f32 v251, -v251, v254, v253
	v_div_fmas_f32 v251, v251, v252, v254
	v_div_fixup_f32 v88, v251, v249, v88
	v_mul_f32_e32 v84, v84, v88
	v_bfe_u32 v88, v84, 16, 1
	v_add3_u32 v84, v84, v88, s33
	global_store_short_d16_hi v250, v84, s[6:7] offset:32
	v_add_u32_e32 v250, 0x21000, v248
	v_mul_f32_e32 v240, 0xbfb8aa3b, v97
	v_mul_f32_e32 v249, 0xbfb8aa3b, v89
	v_exp_f32_e32 v240, v240
	v_exp_f32_e32 v249, v249
	v_add_f32_e32 v240, 1.0, v240
	v_add_f32_e32 v249, 1.0, v249
	v_div_scale_f32 v241, s[8:9], v240, v240, v97
	v_div_scale_f32 v251, s[8:9], v249, v249, v89
	v_rcp_f32_e32 v242, v241
	v_rcp_f32_e32 v252, v251
	v_fma_f32 v243, -v241, v242, 1.0
	v_fma_f32 v253, -v251, v252, 1.0
	v_fmac_f32_e32 v242, v243, v242
	v_fmac_f32_e32 v252, v253, v252
	v_div_scale_f32 v243, vcc, v97, v240, v97
	v_mul_f32_e32 v245, v243, v242
	v_fma_f32 v246, -v241, v245, v243
	v_fmac_f32_e32 v245, v246, v242
	v_fma_f32 v241, -v241, v245, v243
	v_div_fmas_f32 v241, v241, v242, v245
	v_div_fixup_f32 v97, v241, v240, v97
	v_mul_f32_e32 v93, v93, v97
	v_bfe_u32 v97, v93, 16, 1
	v_add3_u32 v93, v93, v97, s33
	global_store_short_d16_hi v250, v93, s[6:7]
	v_div_scale_f32 v253, vcc, v89, v249, v89
	v_mul_f32_e32 v254, v253, v252
	v_fma_f32 v255, -v251, v254, v253
	v_fmac_f32_e32 v254, v255, v252
	v_fma_f32 v251, -v251, v254, v253
	v_div_fmas_f32 v251, v251, v252, v254
	v_div_fixup_f32 v89, v251, v249, v89
	v_mul_f32_e32 v85, v85, v89
	v_bfe_u32 v89, v85, 16, 1
	v_add3_u32 v85, v85, v89, s33
	global_store_short_d16_hi v250, v85, s[6:7] offset:32
	v_add_u32_e32 v250, 0x22000, v248
	v_mul_f32_e32 v240, 0xbfb8aa3b, v98
	v_mul_f32_e32 v249, 0xbfb8aa3b, v90
	v_exp_f32_e32 v240, v240
	v_exp_f32_e32 v249, v249
	v_add_f32_e32 v240, 1.0, v240
	v_add_f32_e32 v249, 1.0, v249
	v_div_scale_f32 v241, s[8:9], v240, v240, v98
	v_div_scale_f32 v251, s[8:9], v249, v249, v90
	v_rcp_f32_e32 v242, v241
	v_rcp_f32_e32 v252, v251
	v_fma_f32 v243, -v241, v242, 1.0
	v_fma_f32 v253, -v251, v252, 1.0
	v_fmac_f32_e32 v242, v243, v242
	v_fmac_f32_e32 v252, v253, v252
	v_div_scale_f32 v243, vcc, v98, v240, v98
	v_mul_f32_e32 v245, v243, v242
	v_fma_f32 v246, -v241, v245, v243
	v_fmac_f32_e32 v245, v246, v242
	v_fma_f32 v241, -v241, v245, v243
	v_div_fmas_f32 v241, v241, v242, v245
	v_div_fixup_f32 v98, v241, v240, v98
	v_mul_f32_e32 v94, v94, v98
	v_bfe_u32 v98, v94, 16, 1
	v_add3_u32 v94, v94, v98, s33
	global_store_short_d16_hi v250, v94, s[6:7]
	v_div_scale_f32 v253, vcc, v90, v249, v90
	v_mul_f32_e32 v254, v253, v252
	v_fma_f32 v255, -v251, v254, v253
	v_fmac_f32_e32 v254, v255, v252
	v_fma_f32 v251, -v251, v254, v253
	v_div_fmas_f32 v251, v251, v252, v254
	v_div_fixup_f32 v90, v251, v249, v90
	v_mul_f32_e32 v86, v86, v90
	v_bfe_u32 v90, v86, 16, 1
	v_add3_u32 v86, v86, v90, s33
	global_store_short_d16_hi v250, v86, s[6:7] offset:32
	v_add_u32_e32 v250, 0x23000, v248
	v_mul_f32_e32 v240, 0xbfb8aa3b, v99
	v_mul_f32_e32 v249, 0xbfb8aa3b, v91
	v_exp_f32_e32 v240, v240
	v_exp_f32_e32 v249, v249
	v_add_f32_e32 v240, 1.0, v240
	v_add_f32_e32 v249, 1.0, v249
	v_div_scale_f32 v241, s[8:9], v240, v240, v99
	v_div_scale_f32 v251, s[8:9], v249, v249, v91
	v_rcp_f32_e32 v242, v241
	v_rcp_f32_e32 v252, v251
	v_fma_f32 v243, -v241, v242, 1.0
	v_fma_f32 v253, -v251, v252, 1.0
	v_fmac_f32_e32 v242, v243, v242
	v_fmac_f32_e32 v252, v253, v252
	v_div_scale_f32 v243, vcc, v99, v240, v99
	v_mul_f32_e32 v245, v243, v242
	v_fma_f32 v246, -v241, v245, v243
	v_fmac_f32_e32 v245, v246, v242
	v_fma_f32 v241, -v241, v245, v243
	v_div_fmas_f32 v241, v241, v242, v245
	v_div_fixup_f32 v99, v241, v240, v99
	v_mul_f32_e32 v95, v95, v99
	v_bfe_u32 v99, v95, 16, 1
	v_add3_u32 v95, v95, v99, s33
	global_store_short_d16_hi v250, v95, s[6:7]
	v_div_scale_f32 v253, vcc, v91, v249, v91
	v_mul_f32_e32 v254, v253, v252
	v_fma_f32 v255, -v251, v254, v253
	v_fmac_f32_e32 v254, v255, v252
	v_fma_f32 v251, -v251, v254, v253
	v_div_fmas_f32 v251, v251, v252, v254
	v_div_fixup_f32 v91, v251, v249, v91
	v_mul_f32_e32 v87, v87, v91
	v_bfe_u32 v91, v87, 16, 1
	v_add3_u32 v87, v87, v91, s33
	global_store_short_d16_hi v250, v87, s[6:7] offset:32
	v_add_u32_e32 v250, 0x30000, v248
	v_mul_f32_e32 v240, 0xbfb8aa3b, v80
	v_mul_f32_e32 v249, 0xbfb8aa3b, v72
	v_exp_f32_e32 v240, v240
	v_exp_f32_e32 v249, v249
	v_add_f32_e32 v240, 1.0, v240
	v_add_f32_e32 v249, 1.0, v249
	v_div_scale_f32 v241, s[8:9], v240, v240, v80
	v_div_scale_f32 v251, s[8:9], v249, v249, v72
	v_rcp_f32_e32 v242, v241
	v_rcp_f32_e32 v252, v251
	v_fma_f32 v243, -v241, v242, 1.0
; __device__ __forceinline__ u16 f2bf(float f) {
;   unsigned u = __float_as_uint(f);
;   u += 0x7fffu + ((u >> 16) & 1u);
;   return (u16)(u >> 16);
; }
; __device__ __forceinline__ float bf2f(u16 h) { return __uint_as_float(((unsigned)h) << 16); }
; __device__ __forceinline__ unsigned pack2(float a, float b) { return (unsigned)f2bf(a) | ((unsigned)f2bf(b) << 16); }
; __device__ __forceinline__ float wave_sum(float v) {
; #pragma unroll
;   for (int o = 32; o > 0; o >>= 1) v += __shfl_xor(v, o);
;   return v;
; }
; __device__ __forceinline__ float siluf(float x) { return x / (1.f + __expf(-x)); }
; __device__ __forceinline__ void moe_up_tile(const Params& p, char* smem, int l, int e, int nt, int b, int mt, bool isctx) {
;     ...
;   auto epi = [&](f32x4 (&acc)[8][4], int wr, int wc, int fr, int fq) {
; #pragma unroll
;     for (int m = 0; m < 8; ++m)
; #pragma unroll
;       for (int j = 0; j < 4; ++j) {
;         int slot = wr * 128 + m * 16 + fq * 4 + j;
;         if (slot < nvalid) {
;           u16* dst = isctx ? ACTC + ((size_t)(((slot >> 5) * 16 + e) * 32 + (slot & 31))) * 2048 : ACTL + (size_t)slot * 2048;
; #pragma unroll
;           for (int n = 0; n < 2; ++n) {
;             int f = nt * 64 + wc * 32 + n * 16 + fr;
;             float g = acc[m][n][j], uu = acc[m][n + 2][j];
;             dst[f] = f2bf(siluf(g) * uu);
;           }
;         }
;       }
;   };
	v_fma_f32 v253, -v251, v252, 1.0
	v_fmac_f32_e32 v242, v243, v242
	v_fmac_f32_e32 v252, v253, v252
	v_div_scale_f32 v243, vcc, v80, v240, v80
	v_mul_f32_e32 v245, v243, v242
	v_fma_f32 v246, -v241, v245, v243
	v_fmac_f32_e32 v245, v246, v242
	v_fma_f32 v241, -v241, v245, v243
	v_div_fmas_f32 v241, v241, v242, v245
	v_div_fixup_f32 v80, v241, v240, v80
	v_mul_f32_e32 v76, v76, v80
	v_bfe_u32 v80, v76, 16, 1
	v_add3_u32 v76, v76, v80, s33
	global_store_short_d16_hi v250, v76, s[6:7]
	v_div_scale_f32 v253, vcc, v72, v249, v72
	v_mul_f32_e32 v254, v253, v252
	v_fma_f32 v255, -v251, v254, v253
	v_fmac_f32_e32 v254, v255, v252
	v_fma_f32 v251, -v251, v254, v253
	v_div_fmas_f32 v251, v251, v252, v254
	v_div_fixup_f32 v72, v251, v249, v72
	v_mul_f32_e32 v68, v68, v72
	v_bfe_u32 v72, v68, 16, 1
	v_add3_u32 v68, v68, v72, s33
	global_store_short_d16_hi v250, v68, s[6:7] offset:32
	v_add_u32_e32 v250, 0x31000, v248
	v_mul_f32_e32 v240, 0xbfb8aa3b, v81
	v_mul_f32_e32 v249, 0xbfb8aa3b, v73
	v_exp_f32_e32 v240, v240
	v_exp_f32_e32 v249, v249
	v_add_f32_e32 v240, 1.0, v240
	v_add_f32_e32 v249, 1.0, v249
	v_div_scale_f32 v241, s[8:9], v240, v240, v81
	v_div_scale_f32 v251, s[8:9], v249, v249, v73
	v_rcp_f32_e32 v242, v241
	v_rcp_f32_e32 v252, v251
	v_fma_f32 v243, -v241, v242, 1.0
	v_fma_f32 v253, -v251, v252, 1.0
	v_fmac_f32_e32 v242, v243, v242
	v_fmac_f32_e32 v252, v253, v252
	v_div_scale_f32 v243, vcc, v81, v240, v81
	v_mul_f32_e32 v245, v243, v242
	v_fma_f32 v246, -v241, v245, v243
	v_fmac_f32_e32 v245, v246, v242
	v_fma_f32 v241, -v241, v245, v243
	v_div_fmas_f32 v241, v241, v242, v245
	v_div_fixup_f32 v81, v241, v240, v81
	v_mul_f32_e32 v77, v77, v81
	v_bfe_u32 v81, v77, 16, 1
	v_add3_u32 v77, v77, v81, s33
	global_store_short_d16_hi v250, v77, s[6:7]
	v_div_scale_f32 v253, vcc, v73, v249, v73
	v_mul_f32_e32 v254, v253, v252
	v_fma_f32 v255, -v251, v254, v253
	v_fmac_f32_e32 v254, v255, v252
	v_fma_f32 v251, -v251, v254, v253
	v_div_fmas_f32 v251, v251, v252, v254
	v_div_fixup_f32 v73, v251, v249, v73
	v_mul_f32_e32 v69, v69, v73
	v_bfe_u32 v73, v69, 16, 1
	v_add3_u32 v69, v69, v73, s33
	global_store_short_d16_hi v250, v69, s[6:7] offset:32
	v_add_u32_e32 v250, 0x32000, v248
	v_mul_f32_e32 v240, 0xbfb8aa3b, v82
	v_mul_f32_e32 v249, 0xbfb8aa3b, v74
	v_exp_f32_e32 v240, v240
	v_exp_f32_e32 v249, v249
	v_add_f32_e32 v240, 1.0, v240
	v_add_f32_e32 v249, 1.0, v249
	v_div_scale_f32 v241, s[8:9], v240, v240, v82
	v_div_scale_f32 v251, s[8:9], v249, v249, v74
	v_rcp_f32_e32 v242, v241
	v_rcp_f32_e32 v252, v251
	v_fma_f32 v243, -v241, v242, 1.0
	v_fma_f32 v253, -v251, v252, 1.0
	v_fmac_f32_e32 v242, v243, v242
	v_fmac_f32_e32 v252, v253, v252
	v_div_scale_f32 v243, vcc, v82, v240, v82
	v_mul_f32_e32 v245, v243, v242
	v_fma_f32 v246, -v241, v245, v243
	v_fmac_f32_e32 v245, v246, v242
	v_fma_f32 v241, -v241, v245, v243
	v_div_fmas_f32 v241, v241, v242, v245
	v_div_fixup_f32 v82, v241, v240, v82
	v_mul_f32_e32 v78, v78, v82
	v_bfe_u32 v82, v78, 16, 1
	v_add3_u32 v78, v78, v82, s33
	global_store_short_d16_hi v250, v78, s[6:7]
	v_div_scale_f32 v253, vcc, v74, v249, v74
	v_mul_f32_e32 v254, v253, v252
	v_fma_f32 v255, -v251, v254, v253
	v_fmac_f32_e32 v254, v255, v252
	v_fma_f32 v251, -v251, v254, v253
	v_div_fmas_f32 v251, v251, v252, v254
	v_div_fixup_f32 v74, v251, v249, v74
	v_mul_f32_e32 v70, v70, v74
	v_bfe_u32 v74, v70, 16, 1
	v_add3_u32 v70, v70, v74, s33
	global_store_short_d16_hi v250, v70, s[6:7] offset:32
	v_add_u32_e32 v250, 0x33000, v248
	v_mul_f32_e32 v240, 0xbfb8aa3b, v83
	v_mul_f32_e32 v249, 0xbfb8aa3b, v75
	v_exp_f32_e32 v240, v240
	v_exp_f32_e32 v249, v249
	v_add_f32_e32 v240, 1.0, v240
	v_add_f32_e32 v249, 1.0, v249
	v_div_scale_f32 v241, s[8:9], v240, v240, v83
	v_div_scale_f32 v251, s[8:9], v249, v249, v75
	v_rcp_f32_e32 v242, v241
	v_rcp_f32_e32 v252, v251
	v_fma_f32 v243, -v241, v242, 1.0
	v_fma_f32 v253, -v251, v252, 1.0
	v_fmac_f32_e32 v242, v243, v242
	v_fmac_f32_e32 v252, v253, v252
	v_div_scale_f32 v243, vcc, v83, v240, v83
	v_mul_f32_e32 v245, v243, v242
	v_fma_f32 v246, -v241, v245, v243
	v_fmac_f32_e32 v245, v246, v242
	v_fma_f32 v241, -v241, v245, v243
	v_div_fmas_f32 v241, v241, v242, v245
	v_div_fixup_f32 v83, v241, v240, v83
	v_mul_f32_e32 v79, v79, v83
	v_bfe_u32 v83, v79, 16, 1
	v_add3_u32 v79, v79, v83, s33
	global_store_short_d16_hi v250, v79, s[6:7]
	v_div_scale_f32 v253, vcc, v75, v249, v75
	v_mul_f32_e32 v254, v253, v252
	v_fma_f32 v255, -v251, v254, v253
	v_fmac_f32_e32 v254, v255, v252
	v_fma_f32 v251, -v251, v254, v253
	v_div_fmas_f32 v251, v251, v252, v254
	v_div_fixup_f32 v75, v251, v249, v75
	v_mul_f32_e32 v71, v71, v75
	v_bfe_u32 v75, v71, 16, 1
	v_add3_u32 v71, v71, v75, s33
	global_store_short_d16_hi v250, v71, s[6:7] offset:32
	v_add_u32_e32 v250, 0x40000, v248
	v_mul_f32_e32 v240, 0xbfb8aa3b, v64
	v_mul_f32_e32 v249, 0xbfb8aa3b, v56
	v_exp_f32_e32 v240, v240
	v_exp_f32_e32 v249, v249
	v_add_f32_e32 v240, 1.0, v240
	v_add_f32_e32 v249, 1.0, v249
	v_div_scale_f32 v241, s[8:9], v240, v240, v64
	v_div_scale_f32 v251, s[8:9], v249, v249, v56
	v_rcp_f32_e32 v242, v241
	v_rcp_f32_e32 v252, v251
	v_fma_f32 v243, -v241, v242, 1.0
	v_fma_f32 v253, -v251, v252, 1.0
	v_fmac_f32_e32 v242, v243, v242
	v_fmac_f32_e32 v252, v253, v252
	v_div_scale_f32 v243, vcc, v64, v240, v64
	v_mul_f32_e32 v245, v243, v242
	v_fma_f32 v246, -v241, v245, v243
	v_fmac_f32_e32 v245, v246, v242
	v_fma_f32 v241, -v241, v245, v243
	v_div_fmas_f32 v241, v241, v242, v245
	v_div_fixup_f32 v64, v241, v240, v64
	v_mul_f32_e32 v60, v60, v64
	v_bfe_u32 v64, v60, 16, 1
	v_add3_u32 v60, v60, v64, s33
	global_store_short_d16_hi v250, v60, s[6:7]
; __device__ __forceinline__ u16 f2bf(float f) {
;   unsigned u = __float_as_uint(f);
;   u += 0x7fffu + ((u >> 16) & 1u);
;   return (u16)(u >> 16);
; }
; __device__ __forceinline__ float bf2f(u16 h) { return __uint_as_float(((unsigned)h) << 16); }
; __device__ __forceinline__ unsigned pack2(float a, float b) { return (unsigned)f2bf(a) | ((unsigned)f2bf(b) << 16); }
; __device__ __forceinline__ float wave_sum(float v) {
; #pragma unroll
;   for (int o = 32; o > 0; o >>= 1) v += __shfl_xor(v, o);
;   return v;
; }
; __device__ __forceinline__ float siluf(float x) { return x / (1.f + __expf(-x)); }
; __device__ __forceinline__ void moe_up_tile(const Params& p, char* smem, int l, int e, int nt, int b, int mt, bool isctx) {
;     ...
;   auto epi = [&](f32x4 (&acc)[8][4], int wr, int wc, int fr, int fq) {
; #pragma unroll
;     for (int m = 0; m < 8; ++m)
; #pragma unroll
;       for (int j = 0; j < 4; ++j) {
;         int slot = wr * 128 + m * 16 + fq * 4 + j;
;         if (slot < nvalid) {
;           u16* dst = isctx ? ACTC + ((size_t)(((slot >> 5) * 16 + e) * 32 + (slot & 31))) * 2048 : ACTL + (size_t)slot * 2048;
; #pragma unroll
;           for (int n = 0; n < 2; ++n) {
;             int f = nt * 64 + wc * 32 + n * 16 + fr;
;             float g = acc[m][n][j], uu = acc[m][n + 2][j];
;             dst[f] = f2bf(siluf(g) * uu);
;           }
;         }
;       }
;   };
	v_div_scale_f32 v253, vcc, v56, v249, v56
	v_mul_f32_e32 v254, v253, v252
	v_fma_f32 v255, -v251, v254, v253
	v_fmac_f32_e32 v254, v255, v252
	v_fma_f32 v251, -v251, v254, v253
	v_div_fmas_f32 v251, v251, v252, v254
	v_div_fixup_f32 v56, v251, v249, v56
	v_mul_f32_e32 v52, v52, v56
	v_bfe_u32 v56, v52, 16, 1
	v_add3_u32 v52, v52, v56, s33
	global_store_short_d16_hi v250, v52, s[6:7] offset:32
	v_add_u32_e32 v250, 0x41000, v248
	v_mul_f32_e32 v240, 0xbfb8aa3b, v65
	v_mul_f32_e32 v249, 0xbfb8aa3b, v57
	v_exp_f32_e32 v240, v240
	v_exp_f32_e32 v249, v249
	v_add_f32_e32 v240, 1.0, v240
	v_add_f32_e32 v249, 1.0, v249
	v_div_scale_f32 v241, s[8:9], v240, v240, v65
	v_div_scale_f32 v251, s[8:9], v249, v249, v57
	v_rcp_f32_e32 v242, v241
	v_rcp_f32_e32 v252, v251
	v_fma_f32 v243, -v241, v242, 1.0
	v_fma_f32 v253, -v251, v252, 1.0
	v_fmac_f32_e32 v242, v243, v242
	v_fmac_f32_e32 v252, v253, v252
	v_div_scale_f32 v243, vcc, v65, v240, v65
	v_mul_f32_e32 v245, v243, v242
	v_fma_f32 v246, -v241, v245, v243
	v_fmac_f32_e32 v245, v246, v242
	v_fma_f32 v241, -v241, v245, v243
	v_div_fmas_f32 v241, v241, v242, v245
	v_div_fixup_f32 v65, v241, v240, v65
	v_mul_f32_e32 v61, v61, v65
	v_bfe_u32 v65, v61, 16, 1
	v_add3_u32 v61, v61, v65, s33
	global_store_short_d16_hi v250, v61, s[6:7]
	v_div_scale_f32 v253, vcc, v57, v249, v57
	v_mul_f32_e32 v254, v253, v252
	v_fma_f32 v255, -v251, v254, v253
	v_fmac_f32_e32 v254, v255, v252
	v_fma_f32 v251, -v251, v254, v253
	v_div_fmas_f32 v251, v251, v252, v254
	v_div_fixup_f32 v57, v251, v249, v57
	v_mul_f32_e32 v53, v53, v57
	v_bfe_u32 v57, v53, 16, 1
	v_add3_u32 v53, v53, v57, s33
	global_store_short_d16_hi v250, v53, s[6:7] offset:32
	v_add_u32_e32 v250, 0x42000, v248
	v_mul_f32_e32 v240, 0xbfb8aa3b, v66
	v_mul_f32_e32 v249, 0xbfb8aa3b, v58
	v_exp_f32_e32 v240, v240
	v_exp_f32_e32 v249, v249
	v_add_f32_e32 v240, 1.0, v240
	v_add_f32_e32 v249, 1.0, v249
	v_div_scale_f32 v241, s[8:9], v240, v240, v66
	v_div_scale_f32 v251, s[8:9], v249, v249, v58
	v_rcp_f32_e32 v242, v241
	v_rcp_f32_e32 v252, v251
	v_fma_f32 v243, -v241, v242, 1.0
	v_fma_f32 v253, -v251, v252, 1.0
	v_fmac_f32_e32 v242, v243, v242
	v_fmac_f32_e32 v252, v253, v252
	v_div_scale_f32 v243, vcc, v66, v240, v66
	v_mul_f32_e32 v245, v243, v242
	v_fma_f32 v246, -v241, v245, v243
	v_fmac_f32_e32 v245, v246, v242
	v_fma_f32 v241, -v241, v245, v243
	v_div_fmas_f32 v241, v241, v242, v245
	v_div_fixup_f32 v66, v241, v240, v66
	v_mul_f32_e32 v62, v62, v66
	v_bfe_u32 v66, v62, 16, 1
	v_add3_u32 v62, v62, v66, s33
	global_store_short_d16_hi v250, v62, s[6:7]
	v_div_scale_f32 v253, vcc, v58, v249, v58
	v_mul_f32_e32 v254, v253, v252
	v_fma_f32 v255, -v251, v254, v253
	v_fmac_f32_e32 v254, v255, v252
	v_fma_f32 v251, -v251, v254, v253
	v_div_fmas_f32 v251, v251, v252, v254
	v_div_fixup_f32 v58, v251, v249, v58
	v_mul_f32_e32 v54, v54, v58
	v_bfe_u32 v58, v54, 16, 1
	v_add3_u32 v54, v54, v58, s33
	global_store_short_d16_hi v250, v54, s[6:7] offset:32
	v_add_u32_e32 v250, 0x43000, v248
	v_mul_f32_e32 v240, 0xbfb8aa3b, v67
	v_mul_f32_e32 v249, 0xbfb8aa3b, v59
	v_exp_f32_e32 v240, v240
	v_exp_f32_e32 v249, v249
	v_add_f32_e32 v240, 1.0, v240
	v_add_f32_e32 v249, 1.0, v249
	v_div_scale_f32 v241, s[8:9], v240, v240, v67
	v_div_scale_f32 v251, s[8:9], v249, v249, v59
	v_rcp_f32_e32 v242, v241
	v_rcp_f32_e32 v252, v251
	v_fma_f32 v243, -v241, v242, 1.0
	v_fma_f32 v253, -v251, v252, 1.0
	v_fmac_f32_e32 v242, v243, v242
	v_fmac_f32_e32 v252, v253, v252
	v_div_scale_f32 v243, vcc, v67, v240, v67
	v_mul_f32_e32 v245, v243, v242
	v_fma_f32 v246, -v241, v245, v243
	v_fmac_f32_e32 v245, v246, v242
	v_fma_f32 v241, -v241, v245, v243
	v_div_fmas_f32 v241, v241, v242, v245
	v_div_fixup_f32 v67, v241, v240, v67
	v_mul_f32_e32 v63, v63, v67
	v_bfe_u32 v67, v63, 16, 1
	v_add3_u32 v63, v63, v67, s33
	global_store_short_d16_hi v250, v63, s[6:7]
	v_div_scale_f32 v253, vcc, v59, v249, v59
	v_mul_f32_e32 v254, v253, v252
	v_fma_f32 v255, -v251, v254, v253
	v_fmac_f32_e32 v254, v255, v252
	v_fma_f32 v251, -v251, v254, v253
	v_div_fmas_f32 v251, v251, v252, v254
	v_div_fixup_f32 v59, v251, v249, v59
	v_mul_f32_e32 v55, v55, v59
	v_bfe_u32 v59, v55, 16, 1
	v_add3_u32 v55, v55, v59, s33
	global_store_short_d16_hi v250, v55, s[6:7] offset:32
	v_add_u32_e32 v250, 0x50000, v248
	v_mul_f32_e32 v240, 0xbfb8aa3b, v48
	v_mul_f32_e32 v249, 0xbfb8aa3b, v40
	v_exp_f32_e32 v240, v240
	v_exp_f32_e32 v249, v249
	v_add_f32_e32 v240, 1.0, v240
	v_add_f32_e32 v249, 1.0, v249
	v_div_scale_f32 v241, s[8:9], v240, v240, v48
	v_div_scale_f32 v251, s[8:9], v249, v249, v40
	v_rcp_f32_e32 v242, v241
	v_rcp_f32_e32 v252, v251
	v_fma_f32 v243, -v241, v242, 1.0
	v_fma_f32 v253, -v251, v252, 1.0
	v_fmac_f32_e32 v242, v243, v242
	v_fmac_f32_e32 v252, v253, v252
	v_div_scale_f32 v243, vcc, v48, v240, v48
	v_mul_f32_e32 v245, v243, v242
	v_fma_f32 v246, -v241, v245, v243
	v_fmac_f32_e32 v245, v246, v242
	v_fma_f32 v241, -v241, v245, v243
	v_div_fmas_f32 v241, v241, v242, v245
	v_div_fixup_f32 v48, v241, v240, v48
	v_mul_f32_e32 v44, v44, v48
	v_bfe_u32 v48, v44, 16, 1
	v_add3_u32 v44, v44, v48, s33
	global_store_short_d16_hi v250, v44, s[6:7]
	v_div_scale_f32 v253, vcc, v40, v249, v40
	v_mul_f32_e32 v254, v253, v252
	v_fma_f32 v255, -v251, v254, v253
	v_fmac_f32_e32 v254, v255, v252
	v_fma_f32 v251, -v251, v254, v253
	v_div_fmas_f32 v251, v251, v252, v254
	v_div_fixup_f32 v40, v251, v249, v40
	v_mul_f32_e32 v36, v36, v40
	v_bfe_u32 v40, v36, 16, 1
	v_add3_u32 v36, v36, v40, s33
	global_store_short_d16_hi v250, v36, s[6:7] offset:32
	v_add_u32_e32 v250, 0x51000, v248
	v_mul_f32_e32 v240, 0xbfb8aa3b, v49
	v_mul_f32_e32 v249, 0xbfb8aa3b, v41
; __device__ __forceinline__ u16 f2bf(float f) {
;   unsigned u = __float_as_uint(f);
;   u += 0x7fffu + ((u >> 16) & 1u);
;   return (u16)(u >> 16);
; }
; __device__ __forceinline__ float bf2f(u16 h) { return __uint_as_float(((unsigned)h) << 16); }
; __device__ __forceinline__ unsigned pack2(float a, float b) { return (unsigned)f2bf(a) | ((unsigned)f2bf(b) << 16); }
; __device__ __forceinline__ float wave_sum(float v) {
; #pragma unroll
;   for (int o = 32; o > 0; o >>= 1) v += __shfl_xor(v, o);
;   return v;
; }
; __device__ __forceinline__ float siluf(float x) { return x / (1.f + __expf(-x)); }
; __device__ __forceinline__ void moe_up_tile(const Params& p, char* smem, int l, int e, int nt, int b, int mt, bool isctx) {
;     ...
;   auto epi = [&](f32x4 (&acc)[8][4], int wr, int wc, int fr, int fq) {
; #pragma unroll
;     for (int m = 0; m < 8; ++m)
; #pragma unroll
;       for (int j = 0; j < 4; ++j) {
;         int slot = wr * 128 + m * 16 + fq * 4 + j;
;         if (slot < nvalid) {
;           u16* dst = isctx ? ACTC + ((size_t)(((slot >> 5) * 16 + e) * 32 + (slot & 31))) * 2048 : ACTL + (size_t)slot * 2048;
; #pragma unroll
;           for (int n = 0; n < 2; ++n) {
;             int f = nt * 64 + wc * 32 + n * 16 + fr;
;             float g = acc[m][n][j], uu = acc[m][n + 2][j];
;             dst[f] = f2bf(siluf(g) * uu);
;           }
;         }
;       }
;   };
	v_exp_f32_e32 v240, v240
	v_exp_f32_e32 v249, v249
	v_add_f32_e32 v240, 1.0, v240
	v_add_f32_e32 v249, 1.0, v249
	v_div_scale_f32 v241, s[8:9], v240, v240, v49
	v_div_scale_f32 v251, s[8:9], v249, v249, v41
	v_rcp_f32_e32 v242, v241
	v_rcp_f32_e32 v252, v251
	v_fma_f32 v243, -v241, v242, 1.0
	v_fma_f32 v253, -v251, v252, 1.0
	v_fmac_f32_e32 v242, v243, v242
	v_fmac_f32_e32 v252, v253, v252
	v_div_scale_f32 v243, vcc, v49, v240, v49
	v_mul_f32_e32 v245, v243, v242
	v_fma_f32 v246, -v241, v245, v243
	v_fmac_f32_e32 v245, v246, v242
	v_fma_f32 v241, -v241, v245, v243
	v_div_fmas_f32 v241, v241, v242, v245
	v_div_fixup_f32 v49, v241, v240, v49
	v_mul_f32_e32 v45, v45, v49
	v_bfe_u32 v49, v45, 16, 1
	v_add3_u32 v45, v45, v49, s33
	global_store_short_d16_hi v250, v45, s[6:7]
	v_div_scale_f32 v253, vcc, v41, v249, v41
	v_mul_f32_e32 v254, v253, v252
	v_fma_f32 v255, -v251, v254, v253
	v_fmac_f32_e32 v254, v255, v252
	v_fma_f32 v251, -v251, v254, v253
	v_div_fmas_f32 v251, v251, v252, v254
	v_div_fixup_f32 v41, v251, v249, v41
	v_mul_f32_e32 v37, v37, v41
	v_bfe_u32 v41, v37, 16, 1
	v_add3_u32 v37, v37, v41, s33
	global_store_short_d16_hi v250, v37, s[6:7] offset:32
	v_add_u32_e32 v250, 0x52000, v248
	v_mul_f32_e32 v240, 0xbfb8aa3b, v50
	v_mul_f32_e32 v249, 0xbfb8aa3b, v42
	v_exp_f32_e32 v240, v240
	v_exp_f32_e32 v249, v249
	v_add_f32_e32 v240, 1.0, v240
	v_add_f32_e32 v249, 1.0, v249
	v_div_scale_f32 v241, s[8:9], v240, v240, v50
	v_div_scale_f32 v251, s[8:9], v249, v249, v42
	v_rcp_f32_e32 v242, v241
	v_rcp_f32_e32 v252, v251
	v_fma_f32 v243, -v241, v242, 1.0
	v_fma_f32 v253, -v251, v252, 1.0
	v_fmac_f32_e32 v242, v243, v242
	v_fmac_f32_e32 v252, v253, v252
	v_div_scale_f32 v243, vcc, v50, v240, v50
	v_mul_f32_e32 v245, v243, v242
	v_fma_f32 v246, -v241, v245, v243
	v_fmac_f32_e32 v245, v246, v242
	v_fma_f32 v241, -v241, v245, v243
	v_div_fmas_f32 v241, v241, v242, v245
	v_div_fixup_f32 v50, v241, v240, v50
	v_mul_f32_e32 v46, v46, v50
	v_bfe_u32 v50, v46, 16, 1
	v_add3_u32 v46, v46, v50, s33
	global_store_short_d16_hi v250, v46, s[6:7]
	v_div_scale_f32 v253, vcc, v42, v249, v42
	v_mul_f32_e32 v254, v253, v252
	v_fma_f32 v255, -v251, v254, v253
	v_fmac_f32_e32 v254, v255, v252
	v_fma_f32 v251, -v251, v254, v253
	v_div_fmas_f32 v251, v251, v252, v254
	v_div_fixup_f32 v42, v251, v249, v42
	v_mul_f32_e32 v38, v38, v42
	v_bfe_u32 v42, v38, 16, 1
	v_add3_u32 v38, v38, v42, s33
	global_store_short_d16_hi v250, v38, s[6:7] offset:32
	v_add_u32_e32 v250, 0x53000, v248
	v_mul_f32_e32 v240, 0xbfb8aa3b, v51
	v_mul_f32_e32 v249, 0xbfb8aa3b, v43
	v_exp_f32_e32 v240, v240
	v_exp_f32_e32 v249, v249
	v_add_f32_e32 v240, 1.0, v240
	v_add_f32_e32 v249, 1.0, v249
	v_div_scale_f32 v241, s[8:9], v240, v240, v51
	v_div_scale_f32 v251, s[8:9], v249, v249, v43
	v_rcp_f32_e32 v242, v241
	v_rcp_f32_e32 v252, v251
	v_fma_f32 v243, -v241, v242, 1.0
	v_fma_f32 v253, -v251, v252, 1.0
	v_fmac_f32_e32 v242, v243, v242
	v_fmac_f32_e32 v252, v253, v252
	v_div_scale_f32 v243, vcc, v51, v240, v51
	v_mul_f32_e32 v245, v243, v242
	v_fma_f32 v246, -v241, v245, v243
	v_fmac_f32_e32 v245, v246, v242
	v_fma_f32 v241, -v241, v245, v243
	v_div_fmas_f32 v241, v241, v242, v245
	v_div_fixup_f32 v51, v241, v240, v51
	v_mul_f32_e32 v47, v47, v51
	v_bfe_u32 v51, v47, 16, 1
	v_add3_u32 v47, v47, v51, s33
	global_store_short_d16_hi v250, v47, s[6:7]
	v_div_scale_f32 v253, vcc, v43, v249, v43
	v_mul_f32_e32 v254, v253, v252
	v_fma_f32 v255, -v251, v254, v253
	v_fmac_f32_e32 v254, v255, v252
	v_fma_f32 v251, -v251, v254, v253
	v_div_fmas_f32 v251, v251, v252, v254
	v_div_fixup_f32 v43, v251, v249, v43
	v_mul_f32_e32 v39, v39, v43
	v_bfe_u32 v43, v39, 16, 1
	v_add3_u32 v39, v39, v43, s33
	global_store_short_d16_hi v250, v39, s[6:7] offset:32
	v_add_u32_e32 v250, 0x60000, v248
	v_mul_f32_e32 v240, 0xbfb8aa3b, v32
	v_mul_f32_e32 v249, 0xbfb8aa3b, v24
	v_exp_f32_e32 v240, v240
	v_exp_f32_e32 v249, v249
	v_add_f32_e32 v240, 1.0, v240
	v_add_f32_e32 v249, 1.0, v249
	v_div_scale_f32 v241, s[8:9], v240, v240, v32
	v_div_scale_f32 v251, s[8:9], v249, v249, v24
	v_rcp_f32_e32 v242, v241
	v_rcp_f32_e32 v252, v251
	v_fma_f32 v243, -v241, v242, 1.0
	v_fma_f32 v253, -v251, v252, 1.0
	v_fmac_f32_e32 v242, v243, v242
	v_fmac_f32_e32 v252, v253, v252
	v_div_scale_f32 v243, vcc, v32, v240, v32
	v_mul_f32_e32 v245, v243, v242
	v_fma_f32 v246, -v241, v245, v243
	v_fmac_f32_e32 v245, v246, v242
	v_fma_f32 v241, -v241, v245, v243
	v_div_fmas_f32 v241, v241, v242, v245
	v_div_fixup_f32 v32, v241, v240, v32
	v_mul_f32_e32 v28, v28, v32
	v_bfe_u32 v32, v28, 16, 1
	v_add3_u32 v28, v28, v32, s33
	global_store_short_d16_hi v250, v28, s[6:7]
	v_div_scale_f32 v253, vcc, v24, v249, v24
	v_mul_f32_e32 v254, v253, v252
	v_fma_f32 v255, -v251, v254, v253
	v_fmac_f32_e32 v254, v255, v252
	v_fma_f32 v251, -v251, v254, v253
	v_div_fmas_f32 v251, v251, v252, v254
	v_div_fixup_f32 v24, v251, v249, v24
	v_mul_f32_e32 v20, v20, v24
	v_bfe_u32 v24, v20, 16, 1
	v_add3_u32 v20, v20, v24, s33
	global_store_short_d16_hi v250, v20, s[6:7] offset:32
	v_add_u32_e32 v250, 0x61000, v248
	v_mul_f32_e32 v240, 0xbfb8aa3b, v33
	v_mul_f32_e32 v249, 0xbfb8aa3b, v25
	v_exp_f32_e32 v240, v240
	v_exp_f32_e32 v249, v249
	v_add_f32_e32 v240, 1.0, v240
	v_add_f32_e32 v249, 1.0, v249
	v_div_scale_f32 v241, s[8:9], v240, v240, v33
	v_div_scale_f32 v251, s[8:9], v249, v249, v25
	v_rcp_f32_e32 v242, v241
	v_rcp_f32_e32 v252, v251
	v_fma_f32 v243, -v241, v242, 1.0
	v_fma_f32 v253, -v251, v252, 1.0
	v_fmac_f32_e32 v242, v243, v242
	v_fmac_f32_e32 v252, v253, v252
	v_div_scale_f32 v243, vcc, v33, v240, v33
	v_mul_f32_e32 v245, v243, v242
	v_fma_f32 v246, -v241, v245, v243
; __device__ __forceinline__ float siluf(float x) { return x / (1.f + __expf(-x)); }
; __device__ __forceinline__ void moe_up_tile(const Params& p, char* smem, int l, int e, int nt, int b, int mt, bool isctx) {
;     ...
;     for (int m = 0; m < 8; ++m)
; #pragma unroll
;       for (int j = 0; j < 4; ++j) {
;         int slot = wr * 128 + m * 16 + fq * 4 + j;
;         if (slot < nvalid) {
;           u16* dst = isctx ? ACTC + ((size_t)(((slot >> 5) * 16 + e) * 32 + (slot & 31))) * 2048 : ACTL + (size_t)slot * 2048;
; #pragma unroll
;           for (int n = 0; n < 2; ++n) {
;             int f = nt * 64 + wc * 32 + n * 16 + fr;
;             float g = acc[m][n][j], uu = acc[m][n + 2][j];
;             dst[f] = f2bf(siluf(g) * uu);
;           }
;         }
	v_fmac_f32_e32 v245, v246, v242
	v_fma_f32 v241, -v241, v245, v243
	v_div_fmas_f32 v241, v241, v242, v245
	v_div_fixup_f32 v33, v241, v240, v33
	v_mul_f32_e32 v29, v29, v33
	v_bfe_u32 v33, v29, 16, 1
	v_add3_u32 v29, v29, v33, s33
	global_store_short_d16_hi v250, v29, s[6:7]
	v_div_scale_f32 v253, vcc, v25, v249, v25
	v_mul_f32_e32 v254, v253, v252
	v_fma_f32 v255, -v251, v254, v253
	v_fmac_f32_e32 v254, v255, v252
	v_fma_f32 v251, -v251, v254, v253
	v_div_fmas_f32 v251, v251, v252, v254
	v_div_fixup_f32 v25, v251, v249, v25
	v_mul_f32_e32 v21, v21, v25
	v_bfe_u32 v25, v21, 16, 1
	v_add3_u32 v21, v21, v25, s33
	global_store_short_d16_hi v250, v21, s[6:7] offset:32
	v_add_u32_e32 v250, 0x62000, v248
	v_mul_f32_e32 v240, 0xbfb8aa3b, v34
	v_mul_f32_e32 v249, 0xbfb8aa3b, v26
	v_exp_f32_e32 v240, v240
	v_exp_f32_e32 v249, v249
	v_add_f32_e32 v240, 1.0, v240
	v_add_f32_e32 v249, 1.0, v249
	v_div_scale_f32 v241, s[8:9], v240, v240, v34
	v_div_scale_f32 v251, s[8:9], v249, v249, v26
	v_rcp_f32_e32 v242, v241
	v_rcp_f32_e32 v252, v251
	v_fma_f32 v243, -v241, v242, 1.0
	v_fma_f32 v253, -v251, v252, 1.0
	v_fmac_f32_e32 v242, v243, v242
	v_fmac_f32_e32 v252, v253, v252
	v_div_scale_f32 v243, vcc, v34, v240, v34
	v_mul_f32_e32 v245, v243, v242
	v_fma_f32 v246, -v241, v245, v243
	v_fmac_f32_e32 v245, v246, v242
	v_fma_f32 v241, -v241, v245, v243
	v_div_fmas_f32 v241, v241, v242, v245
	v_div_fixup_f32 v34, v241, v240, v34
	v_mul_f32_e32 v30, v30, v34
	v_bfe_u32 v34, v30, 16, 1
	v_add3_u32 v30, v30, v34, s33
	global_store_short_d16_hi v250, v30, s[6:7]
	v_div_scale_f32 v253, vcc, v26, v249, v26
	v_mul_f32_e32 v254, v253, v252
	v_fma_f32 v255, -v251, v254, v253
	v_fmac_f32_e32 v254, v255, v252
	v_fma_f32 v251, -v251, v254, v253
	v_div_fmas_f32 v251, v251, v252, v254
	v_div_fixup_f32 v26, v251, v249, v26
	v_mul_f32_e32 v22, v22, v26
	v_bfe_u32 v26, v22, 16, 1
	v_add3_u32 v22, v22, v26, s33
	global_store_short_d16_hi v250, v22, s[6:7] offset:32
	v_add_u32_e32 v250, 0x63000, v248
	v_mul_f32_e32 v240, 0xbfb8aa3b, v35
	v_mul_f32_e32 v249, 0xbfb8aa3b, v27
	v_exp_f32_e32 v240, v240
	v_exp_f32_e32 v249, v249
	v_add_f32_e32 v240, 1.0, v240
	v_add_f32_e32 v249, 1.0, v249
	v_div_scale_f32 v241, s[8:9], v240, v240, v35
	v_div_scale_f32 v251, s[8:9], v249, v249, v27
	v_rcp_f32_e32 v242, v241
	v_rcp_f32_e32 v252, v251
	v_fma_f32 v243, -v241, v242, 1.0
	v_fma_f32 v253, -v251, v252, 1.0
	v_fmac_f32_e32 v242, v243, v242
	v_fmac_f32_e32 v252, v253, v252
	v_div_scale_f32 v243, vcc, v35, v240, v35
	v_mul_f32_e32 v245, v243, v242
	v_fma_f32 v246, -v241, v245, v243
	v_fmac_f32_e32 v245, v246, v242
	v_fma_f32 v241, -v241, v245, v243
	v_div_fmas_f32 v241, v241, v242, v245
	v_div_fixup_f32 v35, v241, v240, v35
	v_mul_f32_e32 v31, v31, v35
	v_bfe_u32 v35, v31, 16, 1
	v_add3_u32 v31, v31, v35, s33
	global_store_short_d16_hi v250, v31, s[6:7]
	v_div_scale_f32 v253, vcc, v27, v249, v27
	v_mul_f32_e32 v254, v253, v252
	v_fma_f32 v255, -v251, v254, v253
	v_fmac_f32_e32 v254, v255, v252
	v_fma_f32 v251, -v251, v254, v253
	v_div_fmas_f32 v251, v251, v252, v254
	v_div_fixup_f32 v27, v251, v249, v27
	v_mul_f32_e32 v23, v23, v27
	v_bfe_u32 v27, v23, 16, 1
	v_add3_u32 v23, v23, v27, s33
	global_store_short_d16_hi v250, v23, s[6:7] offset:32
	v_add_u32_e32 v250, 0x70000, v248
	v_mul_f32_e32 v240, 0xbfb8aa3b, v16
	v_mul_f32_e32 v249, 0xbfb8aa3b, v8
	v_exp_f32_e32 v240, v240
	v_exp_f32_e32 v249, v249
	v_add_f32_e32 v240, 1.0, v240
	v_add_f32_e32 v249, 1.0, v249
	v_div_scale_f32 v241, s[8:9], v240, v240, v16
	v_div_scale_f32 v251, s[8:9], v249, v249, v8
	v_rcp_f32_e32 v242, v241
	v_rcp_f32_e32 v252, v251
	v_fma_f32 v243, -v241, v242, 1.0
	v_fma_f32 v253, -v251, v252, 1.0
	v_fmac_f32_e32 v242, v243, v242
	v_fmac_f32_e32 v252, v253, v252
	v_div_scale_f32 v243, vcc, v16, v240, v16
	v_mul_f32_e32 v245, v243, v242
	v_fma_f32 v246, -v241, v245, v243
	v_fmac_f32_e32 v245, v246, v242
	v_fma_f32 v241, -v241, v245, v243
	v_div_fmas_f32 v241, v241, v242, v245
	v_div_fixup_f32 v16, v241, v240, v16
	v_mul_f32_e32 v12, v12, v16
	v_bfe_u32 v16, v12, 16, 1
	v_add3_u32 v12, v12, v16, s33
	global_store_short_d16_hi v250, v12, s[6:7]
	v_div_scale_f32 v253, vcc, v8, v249, v8
	v_mul_f32_e32 v254, v253, v252
; __device__ __forceinline__ float siluf(float x) { return x / (1.f + __expf(-x)); }
; __device__ __forceinline__ void moe_up_tile(const Params& p, char* smem, int l, int e, int nt, int b, int mt, bool isctx) {
;     ...
;     for (int m = 0; m < 8; ++m)
; #pragma unroll
;       for (int j = 0; j < 4; ++j) {
;         int slot = wr * 128 + m * 16 + fq * 4 + j;
;         if (slot < nvalid) {
;           u16* dst = isctx ? ACTC + ((size_t)(((slot >> 5) * 16 + e) * 32 + (slot & 31))) * 2048 : ACTL + (size_t)slot * 2048;
; #pragma unroll
;           for (int n = 0; n < 2; ++n) {
;             int f = nt * 64 + wc * 32 + n * 16 + fr;
;             float g = acc[m][n][j], uu = acc[m][n + 2][j];
;             dst[f] = f2bf(siluf(g) * uu);
;           }
;         }
	v_fma_f32 v255, -v251, v254, v253
	v_fmac_f32_e32 v254, v255, v252
	v_fma_f32 v251, -v251, v254, v253
	v_div_fmas_f32 v251, v251, v252, v254
	v_div_fixup_f32 v8, v251, v249, v8
	v_mul_f32_e32 v4, v4, v8
	v_bfe_u32 v8, v4, 16, 1
	v_add3_u32 v4, v4, v8, s33
	global_store_short_d16_hi v250, v4, s[6:7] offset:32
	v_add_u32_e32 v250, 0x71000, v248
	v_mul_f32_e32 v240, 0xbfb8aa3b, v17
	v_mul_f32_e32 v249, 0xbfb8aa3b, v9
	v_exp_f32_e32 v240, v240
	v_exp_f32_e32 v249, v249
	v_add_f32_e32 v240, 1.0, v240
	v_add_f32_e32 v249, 1.0, v249
	v_div_scale_f32 v241, s[8:9], v240, v240, v17
	v_div_scale_f32 v251, s[8:9], v249, v249, v9
	v_rcp_f32_e32 v242, v241
	v_rcp_f32_e32 v252, v251
	v_fma_f32 v243, -v241, v242, 1.0
	v_fma_f32 v253, -v251, v252, 1.0
	v_fmac_f32_e32 v242, v243, v242
	v_fmac_f32_e32 v252, v253, v252
	v_div_scale_f32 v243, vcc, v17, v240, v17
	v_mul_f32_e32 v245, v243, v242
	v_fma_f32 v246, -v241, v245, v243
	v_fmac_f32_e32 v245, v246, v242
	v_fma_f32 v241, -v241, v245, v243
	v_div_fmas_f32 v241, v241, v242, v245
	v_div_fixup_f32 v17, v241, v240, v17
	v_mul_f32_e32 v13, v13, v17
	v_bfe_u32 v17, v13, 16, 1
	v_add3_u32 v13, v13, v17, s33
	global_store_short_d16_hi v250, v13, s[6:7]
	v_div_scale_f32 v253, vcc, v9, v249, v9
	v_mul_f32_e32 v254, v253, v252
	v_fma_f32 v255, -v251, v254, v253
	v_fmac_f32_e32 v254, v255, v252
	v_fma_f32 v251, -v251, v254, v253
	v_div_fmas_f32 v251, v251, v252, v254
	v_div_fixup_f32 v9, v251, v249, v9
	v_mul_f32_e32 v5, v5, v9
	v_bfe_u32 v9, v5, 16, 1
	v_add3_u32 v5, v5, v9, s33
	global_store_short_d16_hi v250, v5, s[6:7] offset:32
	v_add_u32_e32 v250, 0x72000, v248
	v_mul_f32_e32 v240, 0xbfb8aa3b, v18
	v_mul_f32_e32 v249, 0xbfb8aa3b, v10
	v_exp_f32_e32 v240, v240
	v_exp_f32_e32 v249, v249
	v_add_f32_e32 v240, 1.0, v240
	v_add_f32_e32 v249, 1.0, v249
	v_div_scale_f32 v241, s[8:9], v240, v240, v18
	v_div_scale_f32 v251, s[8:9], v249, v249, v10
	v_rcp_f32_e32 v242, v241
	v_rcp_f32_e32 v252, v251
	v_fma_f32 v243, -v241, v242, 1.0
	v_fma_f32 v253, -v251, v252, 1.0
	v_fmac_f32_e32 v242, v243, v242
	v_fmac_f32_e32 v252, v253, v252
	v_div_scale_f32 v243, vcc, v18, v240, v18
	v_mul_f32_e32 v245, v243, v242
	v_fma_f32 v246, -v241, v245, v243
	v_fmac_f32_e32 v245, v246, v242
	v_fma_f32 v241, -v241, v245, v243
	v_div_fmas_f32 v241, v241, v242, v245
	v_div_fixup_f32 v18, v241, v240, v18
	v_mul_f32_e32 v14, v14, v18
	v_bfe_u32 v18, v14, 16, 1
	v_add3_u32 v14, v14, v18, s33
	global_store_short_d16_hi v250, v14, s[6:7]
	v_div_scale_f32 v253, vcc, v10, v249, v10
	v_mul_f32_e32 v254, v253, v252
	v_fma_f32 v255, -v251, v254, v253
	v_fmac_f32_e32 v254, v255, v252
	v_fma_f32 v251, -v251, v254, v253
	v_div_fmas_f32 v251, v251, v252, v254
	v_div_fixup_f32 v10, v251, v249, v10
	v_mul_f32_e32 v6, v6, v10
	v_bfe_u32 v10, v6, 16, 1
	v_add3_u32 v6, v6, v10, s33
	global_store_short_d16_hi v250, v6, s[6:7] offset:32
	v_add_u32_e32 v250, 0x73000, v248
	v_mul_f32_e32 v240, 0xbfb8aa3b, v19
	v_mul_f32_e32 v249, 0xbfb8aa3b, v11
	v_exp_f32_e32 v240, v240
	v_exp_f32_e32 v249, v249
	v_add_f32_e32 v240, 1.0, v240
	v_add_f32_e32 v249, 1.0, v249
	v_div_scale_f32 v241, s[8:9], v240, v240, v19
	v_div_scale_f32 v251, s[8:9], v249, v249, v11
	v_rcp_f32_e32 v242, v241
	v_rcp_f32_e32 v252, v251
	v_fma_f32 v243, -v241, v242, 1.0
	v_fma_f32 v253, -v251, v252, 1.0
	v_fmac_f32_e32 v242, v243, v242
	v_fmac_f32_e32 v252, v253, v252
	v_div_scale_f32 v243, vcc, v19, v240, v19
	v_mul_f32_e32 v245, v243, v242
	v_fma_f32 v246, -v241, v245, v243
	v_fmac_f32_e32 v245, v246, v242
	v_fma_f32 v241, -v241, v245, v243
	v_div_fmas_f32 v241, v241, v242, v245
	v_div_fixup_f32 v19, v241, v240, v19
	v_mul_f32_e32 v15, v15, v19
	v_bfe_u32 v19, v15, 16, 1
	v_add3_u32 v15, v15, v19, s33
	global_store_short_d16_hi v250, v15, s[6:7]
	v_div_scale_f32 v253, vcc, v11, v249, v11
	v_mul_f32_e32 v254, v253, v252
	v_fma_f32 v255, -v251, v254, v253
	v_fmac_f32_e32 v254, v255, v252
	v_fma_f32 v251, -v251, v254, v253
	v_div_fmas_f32 v251, v251, v252, v254
	v_div_fixup_f32 v11, v251, v249, v11
	v_mul_f32_e32 v7, v7, v11
	v_bfe_u32 v11, v7, 16, 1
	v_add3_u32 v7, v7, v11, s33
	global_store_short_d16_hi v250, v7, s[6:7] offset:32
	s_mov_b64 s[0:1], exec
	s_branch .LBB0_1639
